# diff fast loop: no full LDS drain at the end of the QK phase; counted lgkmcnt(12) waits before PV MFMAs 1,3,5,7 so PV starts as soon as its first V-transpose reads land
# baseline (speedup 1.0000x reference)
.Lf_459:
	v_mov_b32_e32 v180, v128
	v_mov_b32_e32 v181, v129
	v_mov_b32_e32 v182, v130
	v_mov_b32_e32 v183, v131
	s_waitcnt lgkmcnt(12)
	v_mfma_f32_32x32x16_bf16 v[64:79], v[176:179], v[140:143], v[64:79]
	ds_read_b64_tr_b16 v[128:129], v0 offset:24576
	ds_read_b64_tr_b16 v[130:131], v0 offset:25088
	v_exp_f32_e32 v14, v112
	v_mfma_f32_32x32x16_bf16 v[64:79], v[172:175], v[136:139], v[64:79]
	ds_read_b64_tr_b16 v[172:173], v0 offset:25600
	ds_read_b64_tr_b16 v[174:175], v0 offset:26112
	v_exp_f32_e32 v15, v96
	s_waitcnt lgkmcnt(12)
	v_mfma_f32_32x32x16_bf16 v[64:79], v[168:171], v[132:135], v[64:79]
	ds_read_b64_tr_b16 v[168:169], v0 offset:26624
	ds_read_b64_tr_b16 v[170:171], v0 offset:27136
	v_exp_f32_e32 v96, v113
	v_mfma_f32_32x32x16_bf16 v[64:79], v[164:167], v[180:183], v[64:79]
	ds_read_b64_tr_b16 v[164:165], v0 offset:27648
	ds_read_b64_tr_b16 v[166:167], v0 offset:28160
	v_exp_f32_e32 v97, v97
	s_waitcnt lgkmcnt(12)
	v_mfma_f32_32x32x16_bf16 v[48:63], v[160:163], v[140:143], v[48:63]
	ds_read_b64_tr_b16 v[160:161], v0 offset:28672
	ds_read_b64_tr_b16 v[162:163], v0 offset:29184
	v_exp_f32_e32 v112, v114
	v_mfma_f32_32x32x16_bf16 v[48:63], v[10:13], v[136:139], v[48:63]
	ds_read_b64_tr_b16 v[10:11], v0 offset:29696
	ds_read_b64_tr_b16 v[12:13], v0 offset:30208
	v_exp_f32_e32 v98, v98
	s_waitcnt lgkmcnt(12)
	v_mfma_f32_32x32x16_bf16 v[48:63], v[6:9], v[132:135], v[48:63]
	ds_read_b64_tr_b16 v[6:7], v0 offset:30720
	ds_read_b64_tr_b16 v[8:9], v0 offset:31232
	v_exp_f32_e32 v113, v115
	v_mfma_f32_32x32x16_bf16 v[48:63], v[2:5], v[180:183], v[48:63]
	ds_read_b64_tr_b16 v[2:3], v0 offset:31744
	ds_read_b64_tr_b16 v[4:5], v0 offset:32256
	v_exp_f32_e32 v0, v99
	s_waitcnt lgkmcnt(14)
	v_mfma_f32_32x32x16_bf16 v[32:47], v[128:131], v[140:143], v[32:47]
	v_exp_f32_e32 v99, v116
	v_exp_f32_e32 v100, v100
	v_exp_f32_e32 v114, v117
	s_waitcnt lgkmcnt(12)
	v_mfma_f32_32x32x16_bf16 v[32:47], v[172:175], v[136:139], v[32:47]
	v_exp_f32_e32 v101, v101
	v_exp_f32_e32 v115, v118
	v_exp_f32_e32 v102, v102
	s_waitcnt lgkmcnt(10)
	v_mfma_f32_32x32x16_bf16 v[32:47], v[168:171], v[132:135], v[32:47]
	v_exp_f32_e32 v116, v119
	v_exp_f32_e32 v103, v103
	v_exp_f32_e32 v117, v120
	s_waitcnt lgkmcnt(8)
	v_mfma_f32_32x32x16_bf16 v[32:47], v[164:167], v[180:183], v[32:47]
	v_exp_f32_e32 v104, v104
	v_exp_f32_e32 v118, v121
	v_exp_f32_e32 v105, v105
	s_waitcnt lgkmcnt(6)
	v_mfma_f32_32x32x16_bf16 v[16:31], v[160:163], v[140:143], v[16:31]
	v_exp_f32_e32 v119, v122
	v_exp_f32_e32 v106, v106
	v_exp_f32_e32 v120, v123
	s_waitcnt lgkmcnt(4)
	v_mfma_f32_32x32x16_bf16 v[16:31], v[10:13], v[136:139], v[16:31]
	v_exp_f32_e32 v10, v107
	v_exp_f32_e32 v11, v124
	v_exp_f32_e32 v12, v108
	s_waitcnt lgkmcnt(2)
	v_mfma_f32_32x32x16_bf16 v[16:31], v[6:9], v[132:135], v[16:31]
	v_exp_f32_e32 v6, v125
	v_exp_f32_e32 v7, v109
	v_exp_f32_e32 v8, v126
	s_waitcnt lgkmcnt(0)
	v_mfma_f32_32x32x16_bf16 v[16:31], v[2:5], v[180:183], v[16:31]
	v_exp_f32_e32 v107, v110
	s_nop 0
	v_mfma_f32_4x4x4_16b_bf16 v[84:87], v[218:219], v[140:141], v[84:87]
	v_mfma_f32_4x4x4_16b_bf16 v[88:91], v[218:219], v[142:143], v[88:91]
	v_exp_f32_e32 v108, v127
	v_exp_f32_e32 v109, v111
	v_cvt_pk_bf16_f32 v140, v14, v96
	v_cvt_pk_bf16_f32 v143, v115, v116
	v_mfma_f32_4x4x4_16b_bf16 v[84:87], v[218:219], v[136:137], v[84:87]
	v_mfma_f32_4x4x4_16b_bf16 v[88:91], v[218:219], v[138:139], v[88:91]
	v_cvt_pk_bf16_f32 v128, v104, v105
	v_cvt_pk_bf16_f32 v141, v112, v113
	v_cvt_pk_bf16_f32 v136, v117, v118
	v_mfma_f32_4x4x4_16b_bf16 v[84:87], v[218:219], v[132:133], v[84:87]
	v_mfma_f32_4x4x4_16b_bf16 v[88:91], v[218:219], v[134:135], v[88:91]
	v_cvt_pk_bf16_f32 v137, v119, v120
	v_cvt_pk_bf16_f32 v129, v106, v10
	v_cvt_pk_bf16_f32 v132, v15, v97
	v_cvt_pk_bf16_f32 v130, v12, v7
	v_cvt_pk_bf16_f32 v138, v11, v6
	v_cvt_pk_bf16_f32 v133, v98, v0
	v_cvt_pk_bf16_f32 v142, v99, v114
	v_cvt_pk_bf16_f32 v134, v100, v101
	v_cvt_pk_bf16_f32 v135, v102, v103
	v_cvt_pk_bf16_f32 v139, v8, v108
	v_cvt_pk_bf16_f32 v131, v107, v109
	v_mfma_f32_4x4x4_16b_bf16 v[84:87], v[218:219], v[180:181], v[84:87]
	v_mfma_f32_4x4x4_16b_bf16 v[88:91], v[218:219], v[182:183], v[88:91]
	s_add_i32 s28, s28, 1
	s_add_i32 s13, s13, 1
	s_add_i32 s19, s19, 0x8000
	s_cmpk_eq_i32 s13, 0x45
	s_cbranch_scc1 .Lf_fold464

.Lf_462:
	s_and_b32 s17, s19, 0x18000
	v_add_u32_e32 v0, s17, v227
	v_add_u32_e32 v2, v0, v228
	ds_read_b128 v[96:99], v2
	ds_read_b128 v[100:103], v2 offset:4096
	v_add_u32_e32 v2, v0, v226
	ds_read_b128 v[180:183], v2
	ds_read_b128 v[230:233], v2 offset:4096
	v_add_u32_e32 v2, v0, v225
	v_add_u32_e32 v0, v0, v224
	s_min_u32 s16, s28, 1
	ds_read_b128 v[234:237], v2
	ds_read_b128 v[238:241], v2 offset:4096
	ds_read_b128 v[242:245], v0
	ds_read_b128 v[246:249], v0 offset:4096
	s_lshl_b32 s16, s16, 15
	s_sub_i32 s16, s19, s16
	s_and_b32 s16, s16, 0x18000
	v_add_u32_e32 v0, s16, v195
	s_setprio 1
	s_waitcnt lgkmcnt(6)
	v_mfma_f32_32x32x16_bf16 v[112:127], v[96:99], v[156:159], 0
	s_add_i32 s22, s13, 1
	s_add_i32 s61, s19, 0x8000
	s_add_i32 s20, s61, 0x10000
	s_and_b32 s20, s20, 0x18000
	v_mfma_f32_32x32x16_bf16 v[96:111], v[100:103], v[156:159], 0
	s_add_i32 s20, s20, s23
	s_add_i32 s62, s22, -2
	s_cmpk_gt_u32 s62, 0x41
	s_cselect_b32 s61, 1, 0
	s_waitcnt lgkmcnt(4)
	v_mfma_f32_32x32x16_bf16 v[112:127], v[180:183], v[152:155], v[112:127]
	s_cmp_lt_u32 s62, 62
	s_cselect_b32 s16, 0, 0xffffffc0
	s_cselect_b32 s17, s9, s10
	s_add_i32 s16, s16, s22
	v_mfma_f32_32x32x16_bf16 v[96:111], v[230:233], v[152:155], v[96:111]
	s_lshl_b32 s16, s16, 6
	s_add_i32 s62, s16, s17
	s_ashr_i32 s63, s62, 31
	s_add_u32 s30, s62, s11
	s_waitcnt lgkmcnt(2)
	v_mfma_f32_32x32x16_bf16 v[112:127], v[234:237], v[148:151], v[112:127]
	s_addc_u32 s31, s63, 0
	s_lshl_b64 s[30:31], s[30:31], 7
	s_add_u32 s34, s95, s30
	s_addc_u32 s35, s3, s31
	v_mfma_f32_32x32x16_bf16 v[96:111], v[238:241], v[148:151], v[96:111]
	s_add_u32 s16, s62, s12
	s_addc_u32 s17, s63, 0
	s_lshl_b64 s[16:17], s[16:17], 7
	s_add_u32 s16, s95, s16
	s_waitcnt lgkmcnt(0)
	v_mfma_f32_32x32x16_bf16 v[112:127], v[242:245], v[144:147], v[112:127]
	s_addc_u32 s17, s3, s17
	s_add_u32 s30, s14, s30
	s_addc_u32 s31, s15, s31
	v_mfma_f32_32x32x16_bf16 v[96:111], v[246:249], v[144:147], v[96:111]
	ds_read_b64_tr_b16 v[176:177], v0 offset:16384
	ds_read_b64_tr_b16 v[178:179], v0 offset:16896
	ds_read_b64_tr_b16 v[172:173], v0 offset:17408
	ds_read_b64_tr_b16 v[174:175], v0 offset:17920
	ds_read_b64_tr_b16 v[168:169], v0 offset:18432
	ds_read_b64_tr_b16 v[170:171], v0 offset:18944
	ds_read_b64_tr_b16 v[164:165], v0 offset:19456
	ds_read_b64_tr_b16 v[166:167], v0 offset:19968
	ds_read_b64_tr_b16 v[160:161], v0 offset:20480
	ds_read_b64_tr_b16 v[162:163], v0 offset:20992
	ds_read_b64_tr_b16 v[10:11], v0 offset:21504
	ds_read_b64_tr_b16 v[12:13], v0 offset:22016
	ds_read_b64_tr_b16 v[6:7], v0 offset:22528
	ds_read_b64_tr_b16 v[8:9], v0 offset:23040
	ds_read_b64_tr_b16 v[2:3], v0 offset:23552
	ds_read_b64_tr_b16 v[4:5], v0 offset:24064
	s_setprio 0
	v_max3_f32 v14, v112, v113, v114
	v_max3_f32 v15, v115, v116, v117
	v_max3_f32 v180, v118, v119, v120
	v_max3_f32 v181, v121, v122, v123
	v_max3_f32 v182, v124, v125, v126
	v_max3_f32 v183, v96, v97, v98
	v_max3_f32 v230, v99, v100, v101
	v_max3_f32 v231, v102, v103, v104
	s_nop 0
	v_max3_f32 v14, v14, v15, v180
	v_max3_f32 v232, v105, v106, v107
	v_max3_f32 v15, v181, v182, v127
	v_max3_f32 v233, v108, v109, v110
	v_max3_f32 v180, v183, v230, v231
	v_max3_f32 v181, v232, v233, v111
	s_nop 0
	v_max3_f32 v14, v14, v15, v180
	v_max_f32_e32 v14, v14, v181
	v_mov_b32_e32 v15, v14
	s_nop 1
	v_permlane32_swap_b32_e32 v15, v14
	v_max_f32_e32 v14, v14, v15
	v_cmp_lt_f32_e32 vcc, 0x42800000, v14
	s_cbranch_vccz .Lf_459
	s_branch .Lf_foldrare
.Lf_foldrare:
	s_waitcnt lgkmcnt(0)
	s_nop 4
	v_add_f32_e32 v84, v84, v88
	s_nop 0
	v_mov_b32_e32 v88, v84
	s_nop 1
	v_permlane32_swap_b32_e32 v88, v84
	s_nop 1
	v_add_f32_e32 v80, v84, v88
	s_nop 0
	v_mov_b32_e32 v81, v80
	v_mov_b32_e32 v82, v80
	v_mov_b32_e32 v83, v80
	v_mov_b32_e32 v84, v80
	v_mov_b32_e32 v85, v80
	v_mov_b32_e32 v86, v80
	v_mov_b32_e32 v87, v80
	v_mov_b32_e32 v88, v80
	v_mov_b32_e32 v89, v80
	v_mov_b32_e32 v90, v80
	v_mov_b32_e32 v91, v80
	v_mov_b32_e32 v92, v80
	v_mov_b32_e32 v93, v80
	v_mov_b32_e32 v94, v80
	v_mov_b32_e32 v95, v80
	s_nop 1
	s_branch .Lf_to463
